# weight-conversion tiles (conv_tile) de-serialised: 8 per-thread global loads issued together into distinct VGPRs, LDS writes behind counted vmcnt (9 of 12 inlined copies)
# baseline (speedup 1.0000x reference)
.LBB0_47:
	s_cmpk_gt_i32 s15, 0x7ff
	s_mov_b64 s[6:7], -1
	s_cbranch_scc0 .LBB0_53
	s_cmpk_gt_u32 s15, 0x12ff
	s_cbranch_scc0 .LBB0_50
	s_add_i32 s6, s15, 0xed00
	s_and_b32 s7, s6, 0xffff
	s_mul_i32 s7, s7, 0xba2f
	s_lshr_b32 s16, s7, 16
	s_lshr_b32 s7, s7, 21
	s_mul_i32 s7, s7, 44
	s_sub_i32 s6, s6, s7
	s_and_b32 s7, s16, 0xffe0
	s_lshl_b32 s6, s6, 6
	v_mov_b32_e32 v10, v222
	s_and_b32 s6, s6, 0xffc0
	s_lshl_b32 s16, s7, 2
	v_ashrrev_i32_e32 v8, 5, v10
	v_lshlrev_b32_e32 v0, 2, v10
	s_add_u32 s16, s10, s16
	v_add_u32_e32 v4, s6, v8
	v_and_b32_e32 v0, 0x7c, v0
	s_addc_u32 s17, s11, 0
	v_ashrrev_i32_e32 v5, 31, v4
	v_lshl_add_u64 v[2:3], s[16:17], 0, v[0:1]
	v_lshlrev_b64 v[6:7], 12, v[4:5]
	v_lshl_add_u64 v[6:7], v[2:3], 0, v[6:7]
	s_movk_i32 s18, 0x84
	s_barrier
	global_load_dword v120, v[6:7], off
	v_mad_u64_u32 v[6:7], s[16:17], v8, s18, v[0:1]
	v_add_u32_e32 v8, 8, v4
	v_ashrrev_i32_e32 v9, 31, v8
	v_lshlrev_b64 v[8:9], 12, v[8:9]
	v_lshl_add_u64 v[8:9], v[2:3], 0, v[8:9]
	global_load_dword v121, v[8:9], off
	v_add_u32_e32 v8, 16, v4
	v_ashrrev_i32_e32 v9, 31, v8
	v_lshlrev_b64 v[8:9], 12, v[8:9]
	v_lshl_add_u64 v[8:9], v[2:3], 0, v[8:9]
	s_lshl_b32 s80, s6, 1
	global_load_dword v122, v[8:9], off
	v_add_u32_e32 v8, 24, v4
	v_ashrrev_i32_e32 v9, 31, v8
	v_lshlrev_b64 v[8:9], 12, v[8:9]
	v_lshl_add_u64 v[8:9], v[2:3], 0, v[8:9]
	global_load_dword v123, v[8:9], off
	v_add_u32_e32 v8, 32, v4
	v_ashrrev_i32_e32 v9, 31, v8
	v_lshlrev_b64 v[8:9], 12, v[8:9]
	v_lshl_add_u64 v[8:9], v[2:3], 0, v[8:9]
	global_load_dword v124, v[8:9], off
	v_add_u32_e32 v8, 40, v4
	v_ashrrev_i32_e32 v9, 31, v8
	v_lshlrev_b64 v[8:9], 12, v[8:9]
	v_lshl_add_u64 v[8:9], v[2:3], 0, v[8:9]
	global_load_dword v125, v[8:9], off
	v_add_u32_e32 v8, 48, v4
	v_ashrrev_i32_e32 v9, 31, v8
	v_lshlrev_b64 v[8:9], 12, v[8:9]
	v_lshl_add_u64 v[8:9], v[2:3], 0, v[8:9]
	v_add_u32_e32 v4, 56, v4
	v_ashrrev_i32_e32 v5, 31, v4
	v_lshlrev_b64 v[4:5], 12, v[4:5]
	v_lshl_add_u64 v[2:3], v[2:3], 0, v[4:5]
	global_load_dword v126, v[8:9], off
	global_load_dword v127, v[2:3], off
	v_lshlrev_b32_e32 v2, 3, v10
	v_and_b32_e32 v8, 56, v2
	s_waitcnt vmcnt(7)
	ds_write_b32 v6, v120
	s_waitcnt vmcnt(6)
	ds_write_b32 v6, v121 offset:1056
	s_waitcnt vmcnt(5)
	ds_write_b32 v6, v122 offset:2112
	s_waitcnt vmcnt(4)
	ds_write_b32 v6, v123 offset:3168
	s_waitcnt vmcnt(3)
	ds_write_b32 v6, v124 offset:4224
	s_waitcnt vmcnt(2)
	ds_write_b32 v6, v125 offset:5280
	s_waitcnt vmcnt(1)
	ds_write_b32 v6, v126 offset:6336
	s_waitcnt vmcnt(0)
	ds_write_b32 v6, v127 offset:7392
	v_ashrrev_i32_e32 v0, 3, v10
	v_lshlrev_b32_e32 v2, 2, v0
	v_mad_u32_u24 v6, v8, s18, v2
	s_waitcnt lgkmcnt(0)
	s_barrier
	ds_read2_b32 v[2:3], v6 offset1:33
	ds_read2_b32 v[4:5], v6 offset0:66 offset1:99
	v_add_u32_e32 v0, s7, v0
	s_movk_i32 s7, 0x1600
	s_waitcnt lgkmcnt(1)
	v_cvt_pk_bf16_f32 v2, v2, v3
	s_waitcnt lgkmcnt(0)
	v_cvt_pk_bf16_f32 v3, v4, v5
	ds_read2_b32 v[4:5], v6 offset0:132 offset1:165
	ds_read2_b32 v[6:7], v6 offset0:198 offset1:231
	s_waitcnt lgkmcnt(1)
	v_cvt_pk_bf16_f32 v4, v4, v5
	s_waitcnt lgkmcnt(0)
	v_cvt_pk_bf16_f32 v5, v6, v7
	v_mov_b64_e32 v[6:7], s[4:5]
	v_mad_i64_i32 v[6:7], s[16:17], v0, s7, v[6:7]
	v_lshl_add_u64 v[6:7], v[6:7], 0, s[80:81]
	v_lshlrev_b32_e32 v0, 1, v8
	v_lshl_add_u64 v[6:7], v[6:7], 0, v[0:1]
	global_store_dwordx4 v[6:7], v[2:5], off
	s_mov_b64 s[6:7], 0
.LBB0_50:
	s_andn2_b64 vcc, exec, s[6:7]
	s_cbranch_vccnz .LBB0_52
	s_add_i32 s6, s15, 0xfffff800
	s_and_b32 s80, s6, 0xffffffe0
	s_bitcmp0_b32 s15, 4
	v_readlane_b32 s6, v252, 40
	v_readlane_b32 s7, v252, 42
	s_cselect_b32 s6, s6, s7
	v_readlane_b32 s7, v252, 39
	v_readlane_b32 s16, v252, 41
	s_cselect_b32 s7, s7, s16
	s_add_u32 s18, s7, s9
	s_addc_u32 s19, s6, s8
	s_and_b32 s7, s14, 0x7fffffe0
	s_and_b32 s6, s13, 0x3c0
	v_mov_b32_e32 v8, v222
	s_lshl_b64 s[16:17], s[80:81], 2
	s_add_u32 s16, s18, s16
	v_lshlrev_b32_e32 v0, 2, v8
	v_ashrrev_i32_e32 v6, 5, v8
	v_and_b32_e32 v0, 0x7c, v0
	s_addc_u32 s17, s19, s17
	v_lshl_add_u64 v[2:3], s[16:17], 0, v[0:1]
	v_add_u32_e32 v9, s6, v6
	s_movk_i32 s19, 0x2c00
	v_mad_i64_i32 v[4:5], s[16:17], v9, s19, v[2:3]
	s_barrier
	global_load_dword v120, v[4:5], off
	s_movk_i32 s18, 0x84
	v_mad_u64_u32 v[4:5], s[16:17], v6, s18, v[0:1]
	v_add_u32_e32 v0, 8, v9
	s_lshl_b32 s80, s6, 1
	v_mad_i64_i32 v[6:7], s[16:17], v0, s19, v[2:3]
	global_load_dword v121, v[6:7], off
	v_add_u32_e32 v0, 16, v9
	v_mad_i64_i32 v[6:7], s[16:17], v0, s19, v[2:3]
	global_load_dword v122, v[6:7], off
	v_add_u32_e32 v0, 24, v9
	v_mad_i64_i32 v[6:7], s[16:17], v0, s19, v[2:3]
	global_load_dword v123, v[6:7], off
	v_add_u32_e32 v0, 32, v9
	v_mad_i64_i32 v[6:7], s[16:17], v0, s19, v[2:3]
	global_load_dword v124, v[6:7], off
	v_add_u32_e32 v0, 40, v9
	v_mad_i64_i32 v[6:7], s[16:17], v0, s19, v[2:3]
	global_load_dword v125, v[6:7], off
	v_add_u32_e32 v0, 48, v9
	v_mad_i64_i32 v[6:7], s[16:17], v0, s19, v[2:3]
	global_load_dword v126, v[6:7], off
	v_add_u32_e32 v0, 56, v9
	v_mad_i64_i32 v[2:3], s[16:17], v0, s19, v[2:3]
	global_load_dword v127, v[2:3], off
	v_lshlrev_b32_e32 v2, 3, v8
	v_readlane_b32 s16, v252, 47
	v_readlane_b32 s17, v252, 48
	s_waitcnt vmcnt(7)
	ds_write_b32 v4, v120
	s_waitcnt vmcnt(6)
	ds_write_b32 v4, v121 offset:1056
	s_waitcnt vmcnt(5)
	ds_write_b32 v4, v122 offset:2112
	s_waitcnt vmcnt(4)
	ds_write_b32 v4, v123 offset:3168
	s_waitcnt vmcnt(3)
	ds_write_b32 v4, v124 offset:4224
	s_waitcnt vmcnt(2)
	ds_write_b32 v4, v125 offset:5280
	s_waitcnt vmcnt(1)
	ds_write_b32 v4, v126 offset:6336
	s_waitcnt vmcnt(0)
	ds_write_b32 v4, v127 offset:7392
	v_ashrrev_i32_e32 v0, 3, v8
	v_and_b32_e32 v8, 56, v2
	v_lshlrev_b32_e32 v2, 2, v0
	v_mad_u32_u24 v6, v8, s18, v2
	s_waitcnt lgkmcnt(0)
	s_barrier
	ds_read2_b32 v[2:3], v6 offset1:33
	ds_read2_b32 v[4:5], v6 offset0:66 offset1:99
	s_waitcnt lgkmcnt(1)
	v_cvt_pk_bf16_f32 v2, v2, v3
	s_waitcnt lgkmcnt(0)
	v_cvt_pk_bf16_f32 v3, v4, v5
	ds_read2_b32 v[4:5], v6 offset0:132 offset1:165
	ds_read2_b32 v[6:7], v6 offset0:198 offset1:231
	s_waitcnt lgkmcnt(1)
	v_cvt_pk_bf16_f32 v4, v4, v5
	s_waitcnt lgkmcnt(0)
	v_cvt_pk_bf16_f32 v5, v6, v7
	v_add_u32_e32 v6, s7, v0
	v_ashrrev_i32_e32 v7, 31, v6
	v_lshlrev_b64 v[6:7], 11, v[6:7]
	v_lshl_add_u64 v[6:7], s[16:17], 0, v[6:7]
	v_lshl_add_u64 v[6:7], v[6:7], 0, s[80:81]
	v_lshlrev_b32_e32 v0, 1, v8
	v_lshl_add_u64 v[6:7], v[6:7], 0, v[0:1]
	global_store_dwordx4 v[6:7], v[2:5], off

.LBB0_720:
	s_andn2_b64 vcc, exec, s[0:1]
	s_cbranch_vccnz .LBB0_722
	s_add_i32 s0, s58, 0xffffe160
	s_lshr_b32 s80, s0, 7
	s_and_b32 s25, s0, 0x60
	s_lshl_b64 s[0:1], s[80:81], 20
	s_add_u32 s26, s40, s0
	s_addc_u32 s27, s41, s1
	s_lshl_b64 s[0:1], s[80:81], 19
	s_add_u32 s0, s30, s0
	s_addc_u32 s1, s31, s1
	s_lshl_b32 s24, s58, 6
	v_mov_b32_e32 v10, v222
	s_and_b32 s24, s24, 0x7c0
	s_lshl_b32 s59, s25, 2
	v_ashrrev_i32_e32 v8, 5, v10
	v_lshlrev_b32_e32 v0, 2, v10
	s_add_u32 s26, s26, s59
	v_add_u32_e32 v4, s24, v8
	v_and_b32_e32 v0, 0x7c, v0
	s_addc_u32 s27, s27, 0
	v_ashrrev_i32_e32 v5, 31, v4
	v_lshl_add_u64 v[2:3], s[26:27], 0, v[0:1]
	v_lshlrev_b64 v[6:7], 9, v[4:5]
	v_lshl_add_u64 v[6:7], v[2:3], 0, v[6:7]
	s_movk_i32 s59, 0x84
	s_waitcnt vmcnt(63) expcnt(7) lgkmcnt(15)
	s_barrier
	global_load_dword v120, v[6:7], off
	v_mad_u64_u32 v[6:7], s[26:27], v8, s59, v[0:1]
	v_add_u32_e32 v8, 8, v4
	v_ashrrev_i32_e32 v9, 31, v8
	v_lshlrev_b64 v[8:9], 9, v[8:9]
	v_lshl_add_u64 v[8:9], v[2:3], 0, v[8:9]
	global_load_dword v121, v[8:9], off
	v_add_u32_e32 v8, 16, v4
	v_ashrrev_i32_e32 v9, 31, v8
	v_lshlrev_b64 v[8:9], 9, v[8:9]
	v_lshl_add_u64 v[8:9], v[2:3], 0, v[8:9]
	s_lshl_b32 s80, s24, 1
	global_load_dword v122, v[8:9], off
	v_add_u32_e32 v8, 24, v4
	v_ashrrev_i32_e32 v9, 31, v8
	v_lshlrev_b64 v[8:9], 9, v[8:9]
	v_lshl_add_u64 v[8:9], v[2:3], 0, v[8:9]
	global_load_dword v123, v[8:9], off
	v_add_u32_e32 v8, 32, v4
	v_ashrrev_i32_e32 v9, 31, v8
	v_lshlrev_b64 v[8:9], 9, v[8:9]
	v_lshl_add_u64 v[8:9], v[2:3], 0, v[8:9]
	global_load_dword v124, v[8:9], off
	v_add_u32_e32 v8, 40, v4
	v_ashrrev_i32_e32 v9, 31, v8
	v_lshlrev_b64 v[8:9], 9, v[8:9]
	v_lshl_add_u64 v[8:9], v[2:3], 0, v[8:9]
	global_load_dword v125, v[8:9], off
	v_add_u32_e32 v8, 48, v4
	v_ashrrev_i32_e32 v9, 31, v8
	v_lshlrev_b64 v[8:9], 9, v[8:9]
	v_lshl_add_u64 v[8:9], v[2:3], 0, v[8:9]
	v_add_u32_e32 v4, 56, v4
	v_ashrrev_i32_e32 v5, 31, v4
	v_lshlrev_b64 v[4:5], 9, v[4:5]
	v_lshl_add_u64 v[2:3], v[2:3], 0, v[4:5]
	global_load_dword v126, v[8:9], off
	global_load_dword v127, v[2:3], off
	v_lshlrev_b32_e32 v2, 3, v10
	v_and_b32_e32 v8, 56, v2
	s_waitcnt vmcnt(7)
	ds_write_b32 v6, v120
	s_waitcnt vmcnt(6)
	ds_write_b32 v6, v121 offset:1056
	s_waitcnt vmcnt(5)
	ds_write_b32 v6, v122 offset:2112
	s_waitcnt vmcnt(4)
	ds_write_b32 v6, v123 offset:3168
	s_waitcnt vmcnt(3)
	ds_write_b32 v6, v124 offset:4224
	s_waitcnt vmcnt(2)
	ds_write_b32 v6, v125 offset:5280
	s_waitcnt vmcnt(1)
	ds_write_b32 v6, v126 offset:6336
	s_waitcnt vmcnt(0)
	ds_write_b32 v6, v127 offset:7392
	v_ashrrev_i32_e32 v0, 3, v10
	v_lshlrev_b32_e32 v2, 2, v0
	v_mad_u32_u24 v6, v8, s59, v2
	s_waitcnt lgkmcnt(0)
	s_barrier
	ds_read2_b32 v[2:3], v6 offset1:33
	ds_read2_b32 v[4:5], v6 offset0:66 offset1:99
	s_mov_b32 s59, 0x800000
	s_waitcnt lgkmcnt(1)
	v_cvt_pk_bf16_f32 v2, v2, v3
	s_waitcnt lgkmcnt(0)
	v_cvt_pk_bf16_f32 v3, v4, v5
	ds_read2_b32 v[4:5], v6 offset0:132 offset1:165
	ds_read2_b32 v[6:7], v6 offset0:198 offset1:231
	s_waitcnt lgkmcnt(1)
	v_cvt_pk_bf16_f32 v4, v4, v5
	s_waitcnt lgkmcnt(0)
	v_cvt_pk_bf16_f32 v5, v6, v7
	v_add_u32_e32 v6, s25, v0
	v_ashrrev_i32_e32 v7, 31, v6
	v_lshlrev_b64 v[6:7], 12, v[6:7]
	v_lshl_add_u64 v[6:7], s[0:1], 0, v[6:7]
	v_lshl_add_u64 v[6:7], v[6:7], 0, s[80:81]
	v_lshlrev_b32_e32 v0, 1, v8
	v_lshl_add_u64 v[6:7], v[6:7], 0, v[0:1]
	global_store_dwordx4 v[6:7], v[2:5], off

.LBB0_761:
	s_andn2_b64 vcc, exec, s[0:1]
	s_cbranch_vccnz .LBB0_763
	s_lshl_b32 s0, s58, 1
	s_and_b32 s0, s0, 0x3fe0
	s_add_i32 s80, s0, 0xffffc800
	s_lshl_b32 s0, s58, 6
	v_mov_b32_e32 v10, v222
	s_and_b32 s0, s0, 0x3c0
	s_lshl_b64 s[24:25], s[80:81], 2
	v_ashrrev_i32_e32 v8, 5, v10
	v_lshlrev_b32_e32 v0, 2, v10
	s_add_u32 s24, s46, s24
	v_add_u32_e32 v4, s0, v8
	v_and_b32_e32 v0, 0x7c, v0
	s_addc_u32 s25, s47, s25
	v_ashrrev_i32_e32 v5, 31, v4
	v_lshl_add_u64 v[2:3], s[24:25], 0, v[0:1]
	v_lshlrev_b64 v[6:7], 12, v[4:5]
	v_lshl_add_u64 v[6:7], v[2:3], 0, v[6:7]
	s_movk_i32 s1, 0x84
	s_waitcnt vmcnt(63) expcnt(7) lgkmcnt(15)
	s_barrier
	global_load_dword v120, v[6:7], off
	v_mad_u64_u32 v[6:7], s[24:25], v8, s1, v[0:1]
	v_add_u32_e32 v8, 8, v4
	v_ashrrev_i32_e32 v9, 31, v8
	v_lshlrev_b64 v[8:9], 12, v[8:9]
	v_lshl_add_u64 v[8:9], v[2:3], 0, v[8:9]
	global_load_dword v121, v[8:9], off
	v_add_u32_e32 v8, 16, v4
	v_ashrrev_i32_e32 v9, 31, v8
	v_lshlrev_b64 v[8:9], 12, v[8:9]
	v_lshl_add_u64 v[8:9], v[2:3], 0, v[8:9]
	global_load_dword v122, v[8:9], off
	v_add_u32_e32 v8, 24, v4
	v_ashrrev_i32_e32 v9, 31, v8
	v_lshlrev_b64 v[8:9], 12, v[8:9]
	v_lshl_add_u64 v[8:9], v[2:3], 0, v[8:9]
	global_load_dword v123, v[8:9], off
	v_add_u32_e32 v8, 32, v4
	v_ashrrev_i32_e32 v9, 31, v8
	v_lshlrev_b64 v[8:9], 12, v[8:9]
	v_lshl_add_u64 v[8:9], v[2:3], 0, v[8:9]
	global_load_dword v124, v[8:9], off
	v_add_u32_e32 v8, 40, v4
	v_ashrrev_i32_e32 v9, 31, v8
	v_lshlrev_b64 v[8:9], 12, v[8:9]
	v_lshl_add_u64 v[8:9], v[2:3], 0, v[8:9]
	global_load_dword v125, v[8:9], off
	v_add_u32_e32 v8, 48, v4
	v_ashrrev_i32_e32 v9, 31, v8
	v_lshlrev_b64 v[8:9], 12, v[8:9]
	v_lshl_add_u64 v[8:9], v[2:3], 0, v[8:9]
	v_add_u32_e32 v4, 56, v4
	v_ashrrev_i32_e32 v5, 31, v4
	v_lshlrev_b64 v[4:5], 12, v[4:5]
	v_lshl_add_u64 v[2:3], v[2:3], 0, v[4:5]
	global_load_dword v126, v[8:9], off
	global_load_dword v127, v[2:3], off
	v_lshlrev_b32_e32 v2, 3, v10
	v_and_b32_e32 v8, 56, v2
	s_waitcnt vmcnt(7)
	ds_write_b32 v6, v120
	s_waitcnt vmcnt(6)
	ds_write_b32 v6, v121 offset:1056
	s_waitcnt vmcnt(5)
	ds_write_b32 v6, v122 offset:2112
	s_waitcnt vmcnt(4)
	ds_write_b32 v6, v123 offset:3168
	s_waitcnt vmcnt(3)
	ds_write_b32 v6, v124 offset:4224
	s_waitcnt vmcnt(2)
	ds_write_b32 v6, v125 offset:5280
	s_waitcnt vmcnt(1)
	ds_write_b32 v6, v126 offset:6336
	s_waitcnt vmcnt(0)
	ds_write_b32 v6, v127 offset:7392
	v_ashrrev_i32_e32 v0, 3, v10
	v_lshlrev_b32_e32 v2, 2, v0
	v_mad_u32_u24 v6, v8, s1, v2
	s_waitcnt lgkmcnt(0)
	s_barrier
	ds_read2_b32 v[2:3], v6 offset1:33
	ds_read2_b32 v[4:5], v6 offset0:66 offset1:99
	s_waitcnt lgkmcnt(1)
	v_cvt_pk_bf16_f32 v2, v2, v3
	s_waitcnt lgkmcnt(0)
	v_cvt_pk_bf16_f32 v3, v4, v5
	ds_read2_b32 v[4:5], v6 offset0:132 offset1:165
	ds_read2_b32 v[6:7], v6 offset0:198 offset1:231
	s_waitcnt lgkmcnt(1)
	v_cvt_pk_bf16_f32 v4, v4, v5
	s_waitcnt lgkmcnt(0)
	v_cvt_pk_bf16_f32 v5, v6, v7
	v_add_u32_e32 v6, s80, v0
	v_ashrrev_i32_e32 v7, 31, v6
	v_lshlrev_b64 v[6:7], 11, v[6:7]
	v_lshl_add_u64 v[6:7], s[12:13], 0, v[6:7]
	s_lshl_b32 s80, s0, 1
	v_lshl_add_u64 v[6:7], v[6:7], 0, s[80:81]
	v_lshlrev_b32_e32 v0, 1, v8
	v_lshl_add_u64 v[6:7], v[6:7], 0, v[0:1]
	global_store_dwordx4 v[6:7], v[2:5], off

.LBB0_764:
	s_andn2_b64 vcc, exec, s[0:1]
	s_cbranch_vccnz .LBB0_766
	s_add_i32 s0, s58, 0xffffe800
	s_lshr_b32 s80, s0, 8
	s_lshl_b64 s[0:1], s[80:81], 21
	s_add_u32 s26, s48, s0
	s_addc_u32 s27, s49, s1
	s_lshl_b32 s0, s58, 2
	s_and_b32 s24, s0, 0x3e0
	s_lshl_b64 s[0:1], s[80:81], 20
	s_add_u32 s0, s34, s0
	s_addc_u32 s1, s35, s1
	s_lshl_b32 s25, s58, 6
	v_mov_b32_e32 v10, v222
	s_and_b32 s25, s25, 0x1c0
	s_lshl_b32 s59, s24, 2
	v_ashrrev_i32_e32 v8, 5, v10
	v_lshlrev_b32_e32 v0, 2, v10
	s_add_u32 s26, s26, s59
	v_add_u32_e32 v4, s25, v8
	v_and_b32_e32 v0, 0x7c, v0
	s_addc_u32 s27, s27, 0
	v_ashrrev_i32_e32 v5, 31, v4
	v_lshl_add_u64 v[2:3], s[26:27], 0, v[0:1]
	v_lshlrev_b64 v[6:7], 12, v[4:5]
	v_lshl_add_u64 v[6:7], v[2:3], 0, v[6:7]
	s_movk_i32 s59, 0x84
	s_waitcnt vmcnt(63) expcnt(7) lgkmcnt(15)
	s_barrier
	global_load_dword v120, v[6:7], off
	v_mad_u64_u32 v[6:7], s[26:27], v8, s59, v[0:1]
	v_add_u32_e32 v8, 8, v4
	v_ashrrev_i32_e32 v9, 31, v8
	v_lshlrev_b64 v[8:9], 12, v[8:9]
	v_lshl_add_u64 v[8:9], v[2:3], 0, v[8:9]
	global_load_dword v121, v[8:9], off
	v_add_u32_e32 v8, 16, v4
	v_ashrrev_i32_e32 v9, 31, v8
	v_lshlrev_b64 v[8:9], 12, v[8:9]
	v_lshl_add_u64 v[8:9], v[2:3], 0, v[8:9]
	s_lshl_b32 s80, s25, 1
	global_load_dword v122, v[8:9], off
	v_add_u32_e32 v8, 24, v4
	v_ashrrev_i32_e32 v9, 31, v8
	v_lshlrev_b64 v[8:9], 12, v[8:9]
	v_lshl_add_u64 v[8:9], v[2:3], 0, v[8:9]
	global_load_dword v123, v[8:9], off
	v_add_u32_e32 v8, 32, v4
	v_ashrrev_i32_e32 v9, 31, v8
	v_lshlrev_b64 v[8:9], 12, v[8:9]
	v_lshl_add_u64 v[8:9], v[2:3], 0, v[8:9]
	global_load_dword v124, v[8:9], off
	v_add_u32_e32 v8, 40, v4
	v_ashrrev_i32_e32 v9, 31, v8
	v_lshlrev_b64 v[8:9], 12, v[8:9]
	v_lshl_add_u64 v[8:9], v[2:3], 0, v[8:9]
	global_load_dword v125, v[8:9], off
	v_add_u32_e32 v8, 48, v4
	v_ashrrev_i32_e32 v9, 31, v8
	v_lshlrev_b64 v[8:9], 12, v[8:9]
	v_lshl_add_u64 v[8:9], v[2:3], 0, v[8:9]
	v_add_u32_e32 v4, 56, v4
	v_ashrrev_i32_e32 v5, 31, v4
	v_lshlrev_b64 v[4:5], 12, v[4:5]
	v_lshl_add_u64 v[2:3], v[2:3], 0, v[4:5]
	global_load_dword v126, v[8:9], off
	global_load_dword v127, v[2:3], off
	v_lshlrev_b32_e32 v2, 3, v10
	v_and_b32_e32 v8, 56, v2
	s_waitcnt vmcnt(7)
	ds_write_b32 v6, v120
	s_waitcnt vmcnt(6)
	ds_write_b32 v6, v121 offset:1056
	s_waitcnt vmcnt(5)
	ds_write_b32 v6, v122 offset:2112
	s_waitcnt vmcnt(4)
	ds_write_b32 v6, v123 offset:3168
	s_waitcnt vmcnt(3)
	ds_write_b32 v6, v124 offset:4224
	s_waitcnt vmcnt(2)
	ds_write_b32 v6, v125 offset:5280
	s_waitcnt vmcnt(1)
	ds_write_b32 v6, v126 offset:6336
	s_waitcnt vmcnt(0)
	ds_write_b32 v6, v127 offset:7392
	v_ashrrev_i32_e32 v0, 3, v10
	v_lshlrev_b32_e32 v2, 2, v0
	v_mad_u32_u24 v6, v8, s59, v2
	s_waitcnt lgkmcnt(0)
	s_barrier
	ds_read2_b32 v[2:3], v6 offset1:33
	ds_read2_b32 v[4:5], v6 offset0:66 offset1:99
	s_mov_b32 s59, 0x800000
	s_waitcnt lgkmcnt(1)
	v_cvt_pk_bf16_f32 v2, v2, v3
	s_waitcnt lgkmcnt(0)
	v_cvt_pk_bf16_f32 v3, v4, v5
	ds_read2_b32 v[4:5], v6 offset0:132 offset1:165
	ds_read2_b32 v[6:7], v6 offset0:198 offset1:231
	s_waitcnt lgkmcnt(1)
	v_cvt_pk_bf16_f32 v4, v4, v5
	s_waitcnt lgkmcnt(0)
	v_cvt_pk_bf16_f32 v5, v6, v7
	v_add_u32_e32 v6, s24, v0
	v_ashrrev_i32_e32 v7, 31, v6
	v_lshlrev_b64 v[6:7], 10, v[6:7]
	v_lshl_add_u64 v[6:7], s[0:1], 0, v[6:7]
	v_lshl_add_u64 v[6:7], v[6:7], 0, s[80:81]
	v_lshlrev_b32_e32 v0, 1, v8
	v_lshl_add_u64 v[6:7], v[6:7], 0, v[0:1]
	global_store_dwordx4 v[6:7], v[2:5], off

.LBB0_767:
	s_andn2_b64 vcc, exec, s[0:1]
	s_cbranch_vccnz .LBB0_769
	s_add_i32 s0, s58, 0xfffff000
	s_lshr_b32 s80, s0, 9
	s_lshl_b64 s[0:1], s[80:81], 22
	s_add_u32 s26, s50, s0
	s_addc_u32 s27, s51, s1
	s_lshl_b32 s0, s58, 1
	s_and_b32 s24, s0, 0x3e0
	s_lshl_b64 s[0:1], s[80:81], 21
	s_add_u32 s0, s36, s0
	s_addc_u32 s1, s37, s1
	s_lshl_b32 s25, s58, 6
	v_mov_b32_e32 v10, v222
	s_and_b32 s25, s25, 0x3c0
	s_lshl_b32 s59, s24, 2
	v_ashrrev_i32_e32 v8, 5, v10
	v_lshlrev_b32_e32 v0, 2, v10
	s_add_u32 s26, s26, s59
	v_add_u32_e32 v4, s25, v8
	v_and_b32_e32 v0, 0x7c, v0
	s_addc_u32 s27, s27, 0
	v_ashrrev_i32_e32 v5, 31, v4
	v_lshl_add_u64 v[2:3], s[26:27], 0, v[0:1]
	v_lshlrev_b64 v[6:7], 12, v[4:5]
	v_lshl_add_u64 v[6:7], v[2:3], 0, v[6:7]
	s_movk_i32 s59, 0x84
	s_waitcnt vmcnt(63) expcnt(7) lgkmcnt(15)
	s_barrier
	global_load_dword v120, v[6:7], off
	v_mad_u64_u32 v[6:7], s[26:27], v8, s59, v[0:1]
	v_add_u32_e32 v8, 8, v4
	v_ashrrev_i32_e32 v9, 31, v8
	v_lshlrev_b64 v[8:9], 12, v[8:9]
	v_lshl_add_u64 v[8:9], v[2:3], 0, v[8:9]
	global_load_dword v121, v[8:9], off
	v_add_u32_e32 v8, 16, v4
	v_ashrrev_i32_e32 v9, 31, v8
	v_lshlrev_b64 v[8:9], 12, v[8:9]
	v_lshl_add_u64 v[8:9], v[2:3], 0, v[8:9]
	s_lshl_b32 s80, s25, 1
	global_load_dword v122, v[8:9], off
	v_add_u32_e32 v8, 24, v4
	v_ashrrev_i32_e32 v9, 31, v8
	v_lshlrev_b64 v[8:9], 12, v[8:9]
	v_lshl_add_u64 v[8:9], v[2:3], 0, v[8:9]
	global_load_dword v123, v[8:9], off
	v_add_u32_e32 v8, 32, v4
	v_ashrrev_i32_e32 v9, 31, v8
	v_lshlrev_b64 v[8:9], 12, v[8:9]
	v_lshl_add_u64 v[8:9], v[2:3], 0, v[8:9]
	global_load_dword v124, v[8:9], off
	v_add_u32_e32 v8, 40, v4
	v_ashrrev_i32_e32 v9, 31, v8
	v_lshlrev_b64 v[8:9], 12, v[8:9]
	v_lshl_add_u64 v[8:9], v[2:3], 0, v[8:9]
	global_load_dword v125, v[8:9], off
	v_add_u32_e32 v8, 48, v4
	v_ashrrev_i32_e32 v9, 31, v8
	v_lshlrev_b64 v[8:9], 12, v[8:9]
	v_lshl_add_u64 v[8:9], v[2:3], 0, v[8:9]
	v_add_u32_e32 v4, 56, v4
	v_ashrrev_i32_e32 v5, 31, v4
	v_lshlrev_b64 v[4:5], 12, v[4:5]
	v_lshl_add_u64 v[2:3], v[2:3], 0, v[4:5]
	global_load_dword v126, v[8:9], off
	global_load_dword v127, v[2:3], off
	v_lshlrev_b32_e32 v2, 3, v10
	v_and_b32_e32 v8, 56, v2
	s_waitcnt vmcnt(7)
	ds_write_b32 v6, v120
	s_waitcnt vmcnt(6)
	ds_write_b32 v6, v121 offset:1056
	s_waitcnt vmcnt(5)
	ds_write_b32 v6, v122 offset:2112
	s_waitcnt vmcnt(4)
	ds_write_b32 v6, v123 offset:3168
	s_waitcnt vmcnt(3)
	ds_write_b32 v6, v124 offset:4224
	s_waitcnt vmcnt(2)
	ds_write_b32 v6, v125 offset:5280
	s_waitcnt vmcnt(1)
	ds_write_b32 v6, v126 offset:6336
	s_waitcnt vmcnt(0)
	ds_write_b32 v6, v127 offset:7392
	v_ashrrev_i32_e32 v0, 3, v10
	v_lshlrev_b32_e32 v2, 2, v0
	v_mad_u32_u24 v6, v8, s59, v2
	s_waitcnt lgkmcnt(0)
	s_barrier
	ds_read2_b32 v[2:3], v6 offset1:33
	ds_read2_b32 v[4:5], v6 offset0:66 offset1:99
	s_mov_b32 s59, 0x800000
	s_waitcnt lgkmcnt(1)
	v_cvt_pk_bf16_f32 v2, v2, v3
	s_waitcnt lgkmcnt(0)
	v_cvt_pk_bf16_f32 v3, v4, v5
	ds_read2_b32 v[4:5], v6 offset0:132 offset1:165
	ds_read2_b32 v[6:7], v6 offset0:198 offset1:231
	s_waitcnt lgkmcnt(1)
	v_cvt_pk_bf16_f32 v4, v4, v5
	s_waitcnt lgkmcnt(0)
	v_cvt_pk_bf16_f32 v5, v6, v7
	v_add_u32_e32 v6, s24, v0
	v_ashrrev_i32_e32 v7, 31, v6
	v_lshlrev_b64 v[6:7], 11, v[6:7]
	v_lshl_add_u64 v[6:7], s[0:1], 0, v[6:7]
	v_lshl_add_u64 v[6:7], v[6:7], 0, s[80:81]
	v_lshlrev_b32_e32 v0, 1, v8
	v_lshl_add_u64 v[6:7], v[6:7], 0, v[0:1]
	global_store_dwordx4 v[6:7], v[2:5], off

.LBB0_770:
	s_andn2_b64 vcc, exec, s[0:1]
	s_cbranch_vccnz .LBB0_788
	s_add_i32 s0, s58, 0xfffff800
	s_lshr_b32 s26, s0, 4
	v_readlane_b32 s0, v250, 18
	s_cmp_ge_i32 s26, s0
	s_cselect_b64 s[0:1], -1, 0
	v_cndmask_b32_e64 v0, 0, 1, s[0:1]
	v_readlane_b32 s0, v250, 19
	s_cmp_lt_i32 s26, s0
	v_readfirstlane_b32 s0, v0
	v_readlane_b32 s1, v250, 20
	s_cselect_b32 s0, s0, 2
	s_cmp_lt_i32 s26, s1
	v_readlane_b32 s1, v250, 21
	s_cselect_b32 s0, s0, 3
	s_cmp_lt_i32 s26, s1
	v_readlane_b32 s1, v250, 22
	s_cselect_b32 s0, s0, 4
	s_cmp_lt_i32 s26, s1
	v_readlane_b32 s1, v250, 23
	s_cselect_b32 s0, s0, 5
	s_cmp_lt_i32 s26, s1
	v_readlane_b32 s1, v250, 24
	s_cselect_b32 s0, s0, 6
	s_cmp_lt_i32 s26, s1
	v_readlane_b32 s1, v250, 25
	s_cselect_b32 s0, s0, 7
	s_cmp_lt_i32 s26, s1
	v_readlane_b32 s1, v250, 26
	s_cselect_b32 s0, s0, 8
	s_cmp_lt_i32 s26, s1
	v_readlane_b32 s1, v250, 27
	s_cselect_b32 s0, s0, 9
	s_cmp_lt_i32 s26, s1
	v_readlane_b32 s1, v250, 28
	s_cselect_b32 s0, s0, 10
	s_cmp_lt_i32 s26, s1
	v_readlane_b32 s1, v250, 29
	s_cselect_b32 s0, s0, 11
	s_cmp_lt_i32 s26, s1
	v_readlane_b32 s1, v250, 30
	s_cselect_b32 s0, s0, 12
	s_cmp_lt_i32 s26, s1
	v_readlane_b32 s1, v250, 31
	s_cselect_b32 s0, s0, 13
	s_cmp_lt_i32 s26, s1
	v_readlane_b32 s1, v250, 32
	s_cselect_b32 s0, s0, 14
	s_cmp_lt_i32 s26, s1
	v_readlane_b32 s1, v250, 33
	s_cselect_b32 s0, s0, 15
	s_cmp_lt_i32 s26, s1
	v_readlane_b32 s1, v250, 34
	s_cselect_b32 s0, s0, 16
	s_cmp_lt_i32 s26, s1
	s_cselect_b32 s0, s0, 17
	s_mul_hi_u32 s27, s0, 24
	s_mul_i32 s59, s0, 24
	s_getpc_b64 s[0:1]
	s_add_u32 s0, s0, c_segs@rel32@lo+4
	s_addc_u32 s1, s1, c_segs@rel32@hi+12
	s_add_u32 s0, s0, s59
	s_addc_u32 s1, s1, s27
	s_getpc_b64 s[24:25]
	s_add_u32 s24, s24, c_segs@rel32@lo+20
	s_addc_u32 s25, s25, c_segs@rel32@hi+28
	s_add_u32 s24, s24, s59
	s_addc_u32 s25, s25, s27
	s_load_dword s24, s[24:25], 0x0
	s_nop 0
	s_load_dword s62, s[0:1], 0x0
	v_mov_b32_e32 v4, v222
	v_mov_b32_e32 v6, 0
	v_mov_b32_e32 v7, 0
	s_waitcnt lgkmcnt(0)
	s_cmp_lg_u32 s24, 3
	s_cselect_b64 s[0:1], -1, 0
	s_cmp_lg_u32 s26, 13
	s_cselect_b64 s[24:25], -1, 0
	s_getpc_b64 s[60:61]
	s_add_u32 s60, s60, c_segs@rel32@lo+12
	s_addc_u32 s61, s61, c_segs@rel32@hi+20
	s_add_u32 s60, s60, s59
	s_addc_u32 s61, s61, s27
	s_load_dword s27, s[60:61], 0x0
	s_sub_i32 s59, s26, s62
	s_lshl_b32 s59, s59, 5
	s_waitcnt lgkmcnt(0)
	v_and_b32_e32 v0, 31, v4
	s_add_i32 s60, s59, s27
	v_cmp_gt_u32_e32 vcc, 24, v0
	s_lshl_b32 s27, s58, 6
	s_or_b64 s[24:25], s[24:25], vcc
	s_ashr_i32 s61, s60, 31
	s_and_b32 s27, s27, 0x3c0
	s_and_b64 s[0:1], s[0:1], s[24:25]
	s_lshl_b64 s[24:25], s[60:61], 2
	s_add_u32 s24, s64, s24
	s_addc_u32 s25, s65, s25
	v_lshlrev_b32_e32 v0, 2, v0
	v_ashrrev_i32_e32 v5, 5, v4
	v_lshl_add_u64 v[2:3], s[24:25], 0, v[0:1]
	s_barrier
	s_movk_i32 s62, 0x3ee0
	s_mov_b32 s59, 0x800000
	v_mov_b32_e32 v120, 0
	v_mov_b32_e32 v121, 0
	v_mov_b32_e32 v122, 0
	v_mov_b32_e32 v123, 0
	v_mov_b32_e32 v124, 0
	v_mov_b32_e32 v125, 0
	v_mov_b32_e32 v126, 0
	v_mov_b32_e32 v127, 0
	s_and_saveexec_b64 s[24:25], s[0:1]
	s_cbranch_execz .Lwin_noload
	v_add_u32_e32 v7, s27, v5
	v_mad_i64_i32 v[8:9], s[60:61], v7, s62, v[2:3]
	global_load_dword v120, v[8:9], off
	v_add3_u32 v7, v5, s27, 8
	v_mad_i64_i32 v[8:9], s[60:61], v7, s62, v[2:3]
	global_load_dword v121, v[8:9], off
	v_add3_u32 v7, v5, s27, 16
	v_mad_i64_i32 v[8:9], s[60:61], v7, s62, v[2:3]
	global_load_dword v122, v[8:9], off
	v_add3_u32 v7, v5, s27, 24
	v_mad_i64_i32 v[8:9], s[60:61], v7, s62, v[2:3]
	global_load_dword v123, v[8:9], off
	v_add3_u32 v7, v5, s27, 32
	v_mad_i64_i32 v[8:9], s[60:61], v7, s62, v[2:3]
	global_load_dword v124, v[8:9], off
	v_add3_u32 v7, v5, s27, 40
	v_mad_i64_i32 v[8:9], s[60:61], v7, s62, v[2:3]
	global_load_dword v125, v[8:9], off
	v_add3_u32 v7, v5, s27, 48
	v_mad_i64_i32 v[8:9], s[60:61], v7, s62, v[2:3]
	global_load_dword v126, v[8:9], off
	v_add3_u32 v7, v5, s27, 56
	v_mad_i64_i32 v[8:9], s[60:61], v7, s62, v[2:3]
	global_load_dword v127, v[8:9], off
.Lwin_noload:
	s_or_b64 exec, exec, s[24:25]
	s_movk_i32 s24, 0x84
	v_mul_lo_u32 v8, v5, s24
	v_add_u32_e32 v0, v0, v8
	s_waitcnt vmcnt(7)
	ds_write_b32 v0, v120
	s_waitcnt vmcnt(6)
	ds_write_b32 v0, v121 offset:1056
	s_waitcnt vmcnt(5)
	ds_write_b32 v0, v122 offset:2112
	s_waitcnt vmcnt(4)
	ds_write_b32 v0, v123 offset:3168
	s_waitcnt vmcnt(3)
	ds_write_b32 v0, v124 offset:4224
	s_waitcnt vmcnt(2)
	ds_write_b32 v0, v125 offset:5280
	s_waitcnt vmcnt(1)
	ds_write_b32 v0, v126 offset:6336
	s_waitcnt vmcnt(0)
	ds_write_b32 v0, v127 offset:7392
	v_ashrrev_i32_e32 v0, 3, v4
	v_lshlrev_b32_e32 v2, 3, v4
	v_and_b32_e32 v8, 56, v2
	v_lshlrev_b32_e32 v2, 2, v0
	s_movk_i32 s0, 0x84
	v_mad_u32_u24 v6, v8, s0, v2
	s_waitcnt lgkmcnt(0)
	s_barrier
	ds_read2_b32 v[2:3], v6 offset1:33
	ds_read2_b32 v[4:5], v6 offset0:66 offset1:99
	v_readlane_b32 s0, v252, 47
	v_readlane_b32 s1, v252, 48
	s_lshl_b32 s80, s27, 1
	s_waitcnt lgkmcnt(1)
	v_cvt_pk_bf16_f32 v2, v2, v3
	s_waitcnt lgkmcnt(0)
	v_cvt_pk_bf16_f32 v3, v4, v5
	ds_read2_b32 v[4:5], v6 offset0:132 offset1:165
	ds_read2_b32 v[6:7], v6 offset0:198 offset1:231
	s_waitcnt lgkmcnt(1)
	v_cvt_pk_bf16_f32 v4, v4, v5
	s_waitcnt lgkmcnt(0)
	v_cvt_pk_bf16_f32 v5, v6, v7
	v_lshl_add_u32 v6, s26, 5, v0
	v_ashrrev_i32_e32 v7, 31, v6
	v_lshlrev_b64 v[6:7], 11, v[6:7]
	v_lshl_add_u64 v[6:7], s[0:1], 0, v[6:7]
	v_lshl_add_u64 v[6:7], v[6:7], 0, s[80:81]
	v_lshlrev_b32_e32 v0, 1, v8
	v_lshl_add_u64 v[6:7], v[6:7], 0, v[0:1]
	global_store_dwordx4 v[6:7], v[2:5], off

.LBB0_828:
	s_cmpk_gt_i32 s17, 0x7ff
	s_mov_b64 s[8:9], -1
	s_cbranch_scc0 .LBB0_834
	s_cmpk_gt_u32 s17, 0x12ff
	s_cbranch_scc0 .LBB0_831
	s_add_i32 s8, s17, 0xed00
	s_and_b32 s9, s8, 0xffff
	s_mul_i32 s9, s9, 0xba2f
	s_lshr_b32 s18, s9, 16
	s_lshr_b32 s9, s9, 21
	s_mul_i32 s9, s9, 44
	s_sub_i32 s8, s8, s9
	s_and_b32 s9, s18, 0xffe0
	s_lshl_b32 s8, s8, 6
	v_mov_b32_e32 v10, v222
	s_and_b32 s8, s8, 0xffc0
	s_lshl_b32 s18, s9, 2
	v_ashrrev_i32_e32 v8, 5, v10
	v_lshlrev_b32_e32 v0, 2, v10
	s_add_u32 s18, s12, s18
	v_add_u32_e32 v4, s8, v8
	v_and_b32_e32 v0, 0x7c, v0
	s_addc_u32 s19, s13, 0
	v_ashrrev_i32_e32 v5, 31, v4
	v_lshl_add_u64 v[2:3], s[18:19], 0, v[0:1]
	v_lshlrev_b64 v[6:7], 12, v[4:5]
	v_lshl_add_u64 v[6:7], v[2:3], 0, v[6:7]
	s_movk_i32 s20, 0x84
	s_waitcnt vmcnt(63) expcnt(7) lgkmcnt(15)
	s_barrier
	global_load_dword v120, v[6:7], off
	v_mad_u64_u32 v[6:7], s[18:19], v8, s20, v[0:1]
	v_add_u32_e32 v8, 8, v4
	v_ashrrev_i32_e32 v9, 31, v8
	v_lshlrev_b64 v[8:9], 12, v[8:9]
	v_lshl_add_u64 v[8:9], v[2:3], 0, v[8:9]
	global_load_dword v121, v[8:9], off
	v_add_u32_e32 v8, 16, v4
	v_ashrrev_i32_e32 v9, 31, v8
	v_lshlrev_b64 v[8:9], 12, v[8:9]
	v_lshl_add_u64 v[8:9], v[2:3], 0, v[8:9]
	s_lshl_b32 s80, s8, 1
	global_load_dword v122, v[8:9], off
	v_add_u32_e32 v8, 24, v4
	v_ashrrev_i32_e32 v9, 31, v8
	v_lshlrev_b64 v[8:9], 12, v[8:9]
	v_lshl_add_u64 v[8:9], v[2:3], 0, v[8:9]
	global_load_dword v123, v[8:9], off
	v_add_u32_e32 v8, 32, v4
	v_ashrrev_i32_e32 v9, 31, v8
	v_lshlrev_b64 v[8:9], 12, v[8:9]
	v_lshl_add_u64 v[8:9], v[2:3], 0, v[8:9]
	global_load_dword v124, v[8:9], off
	v_add_u32_e32 v8, 40, v4
	v_ashrrev_i32_e32 v9, 31, v8
	v_lshlrev_b64 v[8:9], 12, v[8:9]
	v_lshl_add_u64 v[8:9], v[2:3], 0, v[8:9]
	global_load_dword v125, v[8:9], off
	v_add_u32_e32 v8, 48, v4
	v_ashrrev_i32_e32 v9, 31, v8
	v_lshlrev_b64 v[8:9], 12, v[8:9]
	v_lshl_add_u64 v[8:9], v[2:3], 0, v[8:9]
	v_add_u32_e32 v4, 56, v4
	v_ashrrev_i32_e32 v5, 31, v4
	v_lshlrev_b64 v[4:5], 12, v[4:5]
	v_lshl_add_u64 v[2:3], v[2:3], 0, v[4:5]
	global_load_dword v126, v[8:9], off
	global_load_dword v127, v[2:3], off
	v_lshlrev_b32_e32 v2, 3, v10
	v_and_b32_e32 v8, 56, v2
	s_waitcnt vmcnt(7)
	ds_write_b32 v6, v120
	s_waitcnt vmcnt(6)
	ds_write_b32 v6, v121 offset:1056
	s_waitcnt vmcnt(5)
	ds_write_b32 v6, v122 offset:2112
	s_waitcnt vmcnt(4)
	ds_write_b32 v6, v123 offset:3168
	s_waitcnt vmcnt(3)
	ds_write_b32 v6, v124 offset:4224
	s_waitcnt vmcnt(2)
	ds_write_b32 v6, v125 offset:5280
	s_waitcnt vmcnt(1)
	ds_write_b32 v6, v126 offset:6336
	s_waitcnt vmcnt(0)
	ds_write_b32 v6, v127 offset:7392
	v_ashrrev_i32_e32 v0, 3, v10
	v_lshlrev_b32_e32 v2, 2, v0
	v_mad_u32_u24 v6, v8, s20, v2
	s_waitcnt lgkmcnt(0)
	s_barrier
	ds_read2_b32 v[2:3], v6 offset1:33
	ds_read2_b32 v[4:5], v6 offset0:66 offset1:99
	v_add_u32_e32 v0, s9, v0
	s_movk_i32 s9, 0x1600
	v_readlane_b32 s20, v252, 52
	s_waitcnt lgkmcnt(1)
	v_cvt_pk_bf16_f32 v2, v2, v3
	s_waitcnt lgkmcnt(0)
	v_cvt_pk_bf16_f32 v3, v4, v5
	ds_read2_b32 v[4:5], v6 offset0:132 offset1:165
	ds_read2_b32 v[6:7], v6 offset0:198 offset1:231
	v_readlane_b32 s21, v252, 53
	s_waitcnt lgkmcnt(1)
	v_cvt_pk_bf16_f32 v4, v4, v5
	s_waitcnt lgkmcnt(0)
	v_cvt_pk_bf16_f32 v5, v6, v7
	v_mov_b64_e32 v[6:7], s[6:7]
	v_mad_i64_i32 v[6:7], s[18:19], v0, s9, v[6:7]
	v_lshl_add_u64 v[6:7], v[6:7], 0, s[80:81]
	v_lshlrev_b32_e32 v0, 1, v8
	v_lshl_add_u64 v[6:7], v[6:7], 0, v[0:1]
	global_store_dwordx4 v[6:7], v[2:5], off
	s_mov_b64 s[8:9], 0
.LBB0_831:
	s_andn2_b64 vcc, exec, s[8:9]
	s_cbranch_vccnz .LBB0_833
	s_add_i32 s8, s17, 0xfffff800
	s_and_b32 s80, s8, 0xffffffe0
	s_bitcmp0_b32 s17, 4
	v_readlane_b32 s8, v252, 40
	v_readlane_b32 s9, v252, 42
	s_cselect_b32 s8, s8, s9
	v_readlane_b32 s9, v252, 39
	v_readlane_b32 s18, v252, 41
	s_cselect_b32 s9, s9, s18
	s_add_u32 s20, s9, s10
	s_addc_u32 s21, s8, s11
	s_and_b32 s9, s16, 0x7fffffe0
	s_and_b32 s8, s15, 0x3c0
	v_mov_b32_e32 v8, v222
	s_lshl_b64 s[18:19], s[80:81], 2
	s_add_u32 s18, s20, s18
	v_lshlrev_b32_e32 v0, 2, v8
	v_ashrrev_i32_e32 v6, 5, v8
	v_and_b32_e32 v0, 0x7c, v0
	s_addc_u32 s19, s21, s19
	v_lshl_add_u64 v[2:3], s[18:19], 0, v[0:1]
	v_add_u32_e32 v9, s8, v6
	s_movk_i32 s21, 0x2c00
	v_mad_i64_i32 v[4:5], s[18:19], v9, s21, v[2:3]
	s_waitcnt vmcnt(63) expcnt(7) lgkmcnt(15)
	s_barrier
	global_load_dword v120, v[4:5], off
	s_movk_i32 s20, 0x84
	v_mad_u64_u32 v[4:5], s[18:19], v6, s20, v[0:1]
	v_add_u32_e32 v0, 8, v9
	s_lshl_b32 s80, s8, 1
	v_mad_i64_i32 v[6:7], s[18:19], v0, s21, v[2:3]
	global_load_dword v121, v[6:7], off
	v_add_u32_e32 v0, 16, v9
	v_mad_i64_i32 v[6:7], s[18:19], v0, s21, v[2:3]
	global_load_dword v122, v[6:7], off
	v_add_u32_e32 v0, 24, v9
	v_mad_i64_i32 v[6:7], s[18:19], v0, s21, v[2:3]
	global_load_dword v123, v[6:7], off
	v_add_u32_e32 v0, 32, v9
	v_mad_i64_i32 v[6:7], s[18:19], v0, s21, v[2:3]
	global_load_dword v124, v[6:7], off
	v_add_u32_e32 v0, 40, v9
	v_mad_i64_i32 v[6:7], s[18:19], v0, s21, v[2:3]
	global_load_dword v125, v[6:7], off
	v_add_u32_e32 v0, 48, v9
	v_mad_i64_i32 v[6:7], s[18:19], v0, s21, v[2:3]
	global_load_dword v126, v[6:7], off
	v_add_u32_e32 v0, 56, v9
	v_mad_i64_i32 v[2:3], s[18:19], v0, s21, v[2:3]
	global_load_dword v127, v[2:3], off
	v_lshlrev_b32_e32 v2, 3, v8
	v_readlane_b32 s18, v252, 47
	v_readlane_b32 s19, v252, 48
	s_waitcnt vmcnt(7)
	ds_write_b32 v4, v120
	s_waitcnt vmcnt(6)
	ds_write_b32 v4, v121 offset:1056
	s_waitcnt vmcnt(5)
	ds_write_b32 v4, v122 offset:2112
	s_waitcnt vmcnt(4)
	ds_write_b32 v4, v123 offset:3168
	s_waitcnt vmcnt(3)
	ds_write_b32 v4, v124 offset:4224
	s_waitcnt vmcnt(2)
	ds_write_b32 v4, v125 offset:5280
	s_waitcnt vmcnt(1)
	ds_write_b32 v4, v126 offset:6336
	s_waitcnt vmcnt(0)
	ds_write_b32 v4, v127 offset:7392
	v_ashrrev_i32_e32 v0, 3, v8
	v_and_b32_e32 v8, 56, v2
	v_lshlrev_b32_e32 v2, 2, v0
	v_mad_u32_u24 v6, v8, s20, v2
	s_waitcnt lgkmcnt(0)
	s_barrier
	ds_read2_b32 v[2:3], v6 offset1:33
	ds_read2_b32 v[4:5], v6 offset0:66 offset1:99
	v_readlane_b32 s20, v252, 52
	v_readlane_b32 s21, v252, 53
	s_waitcnt lgkmcnt(1)
	v_cvt_pk_bf16_f32 v2, v2, v3
	s_waitcnt lgkmcnt(0)
	v_cvt_pk_bf16_f32 v3, v4, v5
	ds_read2_b32 v[4:5], v6 offset0:132 offset1:165
	ds_read2_b32 v[6:7], v6 offset0:198 offset1:231
	s_waitcnt lgkmcnt(1)
	v_cvt_pk_bf16_f32 v4, v4, v5
	s_waitcnt lgkmcnt(0)
	v_cvt_pk_bf16_f32 v5, v6, v7
	v_add_u32_e32 v6, s9, v0
	v_ashrrev_i32_e32 v7, 31, v6
	v_lshlrev_b64 v[6:7], 11, v[6:7]
	v_lshl_add_u64 v[6:7], s[18:19], 0, v[6:7]
	v_lshl_add_u64 v[6:7], v[6:7], 0, s[80:81]
	v_lshlrev_b32_e32 v0, 1, v8
	v_lshl_add_u64 v[6:7], v[6:7], 0, v[0:1]
	global_store_dwordx4 v[6:7], v[2:5], off
